# GEMM MFMA blocks as accumulate chains (8 once-per-unit blocks keep hipcc order), barrier-to-first-MFMA path shortened, P4 epilogue alignment barrier behind the row-scale loads
# baseline (speedup 1.0000x reference)
; #define PG8_STAGE(bufoff, gbase, voff) do { if constexpr (ABL & 1) break; glds16s<(bufoff)>((voff)[0], (const void*)(gbase), ldsbw); glds16s<(bufoff) + 8192>((voff)[1], (const void*)(gbase), ldsbw); } while (0)
; #define PG8_LDA(dst, b, h) do { if constexpr (ABL & 4) break; _Pragma("unroll") for (int m = 0; m < 4; ++m) _Pragma("unroll") for (int k = 0; k < 2; ++k) dst[m][k] = *(const LAS f16x8*)(lds + PG8_SA(b, h) + aoff + m * 2048 + k * 1024); } while (0)
; #define PG8_LDB(dst, b, h) do { if constexpr (ABL & 4) break; _Pragma("unroll") for (int n = 0; n < 2; ++n) _Pragma("unroll") for (int k = 0; k < 2; ++k) dst[n][k] = *(const LAS f16x8*)(lds + PG8_SB(b, h) + boff + n * 2048 + k * 1024); } while (0)
; #define PG8_MMAF(ai, bj, At, Bt) do { if (t == 0) PG8_MMA0(ai, bj, At, Bt); else PG8_MMA(ai, bj, At, Bt); } while (0)
; #define PG8_WAIT_V(n) asm volatile("s_waitcnt vmcnt(" #n ")" ::: "memory")
; #define PG8_WAIT_L(n) asm volatile("s_waitcnt lgkmcnt(" #n ")" ::: "memory")
; #define PG8_BAR __builtin_amdgcn_s_barrier()
; #define PG8_SCHED __builtin_amdgcn_sched_barrier(0)
;     ...
;             PG8_LDB(B0, 0, 0); PG8_LDB(B1, 0, 1); PG8_SCHED; PG8_LDA(At, 0, 0); PG8_STAGE(PG8_SA(1, 1), a1 + hstep, voffA);
;             PG8_WAIT_V(8); PG8_WAIT_L(0); PG8_BAR; PG8_MMAF(0, 0, At, B0); PG8_MMAF(0, 1, At, B1); PG8_BAR; PG8_SCHED;
;             const bool fin = last && !has_next;
;             PG8_LDA(At, 0, 1); if (!fin) { PG8_STAGE(PG8_SB(0, 0), b2, voffB); PG8_STAGE(PG8_SB(0, 1), b2 + hstep, voffB); PG8_STAGE(PG8_SA(0, 0), a2, voffA); }
;             if (!fin) PG8_WAIT_V(8); else PG8_WAIT_V(2); PG8_WAIT_L(0); PG8_BAR; PG8_MMAF(1, 0, At, B0); PG8_MMAF(1, 1, At, B1); PG8_BAR; PG8_SCHED;
.LBB0_229:
	s_ashr_i32 s53, s52, 31
	s_lshl_b64 s[8:9], s[52:53], 19
	s_add_u32 s54, s74, s8
	s_addc_u32 s55, s75, s9
	s_and_b64 s[8:9], exec, s[4:5]
	ds_read_b128 v[2:5], v236
	ds_read_b128 v[6:9], v236 offset:1024
	ds_read_b128 v[10:13], v236 offset:2048
	ds_read_b128 v[14:17], v236 offset:3072
	ds_read_b128 v[18:21], v237
	ds_read_b128 v[22:25], v237 offset:1024
	ds_read_b128 v[26:29], v237 offset:2048
	ds_read_b128 v[30:33], v237 offset:3072
	s_cselect_b32 s11, s63, s55
	s_cselect_b32 s35, s62, s54
	s_ashr_i32 s1, s0, 31
	s_lshl_b64 s[8:9], s[0:1], 19
	s_add_u32 s56, s90, s8
	s_addc_u32 s57, s91, s9
	s_and_b64 s[8:9], exec, s[4:5]
	s_cselect_b32 s1, s7, s57
	s_cselect_b32 s46, s6, s56
	s_add_u32 s8, s62, 0x100
	s_addc_u32 s9, s63, 0
	s_add_u32 s64, s6, 0x100
	s_addc_u32 s65, s7, 0
	s_add_u32 s24, s62, 0x180
	s_addc_u32 s25, s63, 0
	ds_read_b128 v[34:37], v238
	ds_read_b128 v[38:41], v238 offset:1024
	ds_read_b128 v[42:45], v238 offset:2048
	ds_read_b128 v[46:49], v238 offset:3072
	ds_read_b128 v[50:53], v238 offset:4096
	ds_read_b128 v[54:57], v238 offset:5120
	ds_read_b128 v[58:61], v238 offset:6144
	ds_read_b128 v[62:65], v238 offset:7168
	s_add_u32 s26, s6, 0x180
	s_addc_u32 s27, s7, 0
	s_add_u32 s76, s62, 0x40080
	s_addc_u32 s77, s63, 0
	s_add_u32 m0, s28, 0xc000
	s_nop 0
	global_load_lds_dwordx4 v232, s[76:77]
	s_nop 0
	s_add_u32 m0, s28, 0xe000
	s_nop 0
	global_load_lds_dwordx4 v234, s[76:77]
	s_waitcnt vmcnt(8)
	s_waitcnt lgkmcnt(0)
	s_barrier
	v_mfma_f32_16x16x32_f16 v[86:89], v[10:13], v[50:53], 0
	s_setprio 1
	v_mfma_f32_16x16x32_f16 v[90:93], v[14:17], v[54:57], v[86:89]
	v_mfma_f32_16x16x32_f16 v[86:89], v[2:5], v[58:61], 0
	v_mfma_f32_16x16x32_f16 v[94:97], v[6:9], v[62:65], v[86:89]
	v_mfma_f32_16x16x32_f16 v[66:69], v[2:5], v[34:37], 0
	v_mfma_f32_16x16x32_f16 v[66:69], v[6:9], v[38:41], v[66:69]
	v_mfma_f32_16x16x32_f16 v[70:73], v[10:13], v[34:37], 0
	v_mfma_f32_16x16x32_f16 v[70:73], v[14:17], v[38:41], v[70:73]
	v_mfma_f32_16x16x32_f16 v[74:77], v[2:5], v[42:45], 0
	v_mfma_f32_16x16x32_f16 v[74:77], v[6:9], v[46:49], v[74:77]
	v_mfma_f32_16x16x32_f16 v[78:81], v[10:13], v[42:45], 0
	v_mfma_f32_16x16x32_f16 v[78:81], v[14:17], v[46:49], v[78:81]
	v_mfma_f32_16x16x32_f16 v[82:85], v[2:5], v[50:53], 0
	v_mfma_f32_16x16x32_f16 v[82:85], v[6:9], v[54:57], v[82:85]
	v_mfma_f32_16x16x32_f16 v[86:89], v[10:13], v[58:61], 0
	v_mfma_f32_16x16x32_f16 v[106:109], v[14:17], v[62:65], v[86:89]
	v_mfma_f32_16x16x32_f16 v[86:89], v[18:21], v[34:37], 0
	v_mfma_f32_16x16x32_f16 v[34:37], v[26:29], v[34:37], 0
	v_mfma_f32_16x16x32_f16 v[110:113], v[22:25], v[38:41], v[86:89]
	v_mfma_f32_16x16x32_f16 v[34:37], v[30:33], v[38:41], v[34:37]
	v_mfma_f32_16x16x32_f16 v[38:41], v[18:21], v[42:45], 0
	v_mfma_f32_16x16x32_f16 v[42:45], v[26:29], v[42:45], 0
	v_mfma_f32_16x16x32_f16 v[38:41], v[22:25], v[46:49], v[38:41]
	v_mfma_f32_16x16x32_f16 v[42:45], v[30:33], v[46:49], v[42:45]
	v_mfma_f32_16x16x32_f16 v[46:49], v[18:21], v[50:53], 0
	v_mfma_f32_16x16x32_f16 v[50:53], v[26:29], v[50:53], 0
	v_mfma_f32_16x16x32_f16 v[46:49], v[22:25], v[54:57], v[46:49]
	v_mfma_f32_16x16x32_f16 v[54:57], v[30:33], v[54:57], v[50:53]
	v_mfma_f32_16x16x32_f16 v[50:53], v[18:21], v[58:61], 0
	v_mfma_f32_16x16x32_f16 v[130:133], v[22:25], v[62:65], v[50:53]
	v_mfma_f32_16x16x32_f16 v[50:53], v[26:29], v[58:61], 0
	v_mfma_f32_16x16x32_f16 v[62:65], v[30:33], v[62:65], v[50:53]
	s_barrier
	s_setprio 0
	s_nop 4
	ds_read_b128 v[50:53], v238 offset:16384
	ds_read_b128 v[58:61], v238 offset:17408
	ds_read_b128 v[86:89], v238 offset:18432
	ds_read_b128 v[98:101], v238 offset:19456
	ds_read_b128 v[102:105], v238 offset:20480
	ds_read_b128 v[114:117], v238 offset:21504
	ds_read_b128 v[118:121], v238 offset:22528
	ds_read_b128 v[122:125], v238 offset:23552
	s_add_u32 m0, s28, 0x10000
	s_nop 0
	global_load_lds_dwordx4 v233, s[64:65]
	s_nop 0
	s_add_u32 m0, s28, 0x12000
	s_nop 0
	global_load_lds_dwordx4 v235, s[64:65]
	s_add_u32 s64, s6, 0x40100
	s_addc_u32 s65, s7, 0
	s_add_u32 m0, s28, 0x14000
	s_nop 0
	global_load_lds_dwordx4 v233, s[64:65]
	s_nop 0
	s_add_u32 m0, s28, 0x16000
	s_nop 0
	global_load_lds_dwordx4 v235, s[64:65]
	s_nop 0
	s_add_u32 m0, s28, 0
	s_nop 0
	global_load_lds_dwordx4 v232, s[8:9]
	s_nop 0
	s_add_u32 m0, s28, 0x2000
	s_nop 0
	global_load_lds_dwordx4 v234, s[8:9]
	s_waitcnt vmcnt(8)
	s_waitcnt lgkmcnt(0)
	s_barrier
	v_mfma_f32_16x16x32_f16 v[126:129], v[2:5], v[50:53], 0
	s_setprio 1
	v_mfma_f32_16x16x32_f16 v[134:137], v[6:9], v[58:61], v[126:129]
	v_mfma_f32_16x16x32_f16 v[126:129], v[10:13], v[50:53], 0
	v_mfma_f32_16x16x32_f16 v[138:141], v[14:17], v[58:61], v[126:129]
	v_mfma_f32_16x16x32_f16 v[126:129], v[2:5], v[86:89], 0
	v_mfma_f32_16x16x32_f16 v[142:145], v[6:9], v[98:101], v[126:129]
	v_mfma_f32_16x16x32_f16 v[126:129], v[10:13], v[86:89], 0
	v_mfma_f32_16x16x32_f16 v[146:149], v[14:17], v[98:101], v[126:129]
	v_mfma_f32_16x16x32_f16 v[126:129], v[2:5], v[102:105], 0
	v_mfma_f32_16x16x32_f16 v[150:153], v[6:9], v[114:117], v[126:129]
	v_mfma_f32_16x16x32_f16 v[2:5], v[2:5], v[118:121], 0
	v_mfma_f32_16x16x32_f16 v[2:5], v[6:9], v[122:125], v[2:5]
	v_mfma_f32_16x16x32_f16 v[6:9], v[10:13], v[118:121], 0
	v_mfma_f32_16x16x32_f16 v[126:129], v[10:13], v[102:105], 0
	v_mfma_f32_16x16x32_f16 v[154:157], v[14:17], v[114:117], v[126:129]
	v_mfma_f32_16x16x32_f16 v[10:13], v[14:17], v[122:125], v[6:9]
	v_mfma_f32_16x16x32_f16 v[6:9], v[18:21], v[50:53], 0
	v_mfma_f32_16x16x32_f16 v[158:161], v[22:25], v[58:61], v[6:9]
	v_mfma_f32_16x16x32_f16 v[6:9], v[26:29], v[50:53], 0
	v_mfma_f32_16x16x32_f16 v[162:165], v[30:33], v[58:61], v[6:9]
	v_mfma_f32_16x16x32_f16 v[6:9], v[18:21], v[86:89], 0
	v_mfma_f32_16x16x32_f16 v[166:169], v[22:25], v[98:101], v[6:9]
	v_mfma_f32_16x16x32_f16 v[6:9], v[26:29], v[86:89], 0
	v_mfma_f32_16x16x32_f16 v[170:173], v[30:33], v[98:101], v[6:9]
	v_mfma_f32_16x16x32_f16 v[6:9], v[18:21], v[102:105], 0
	v_mfma_f32_16x16x32_f16 v[174:177], v[22:25], v[114:117], v[6:9]
	v_mfma_f32_16x16x32_f16 v[6:9], v[26:29], v[102:105], 0
	v_mfma_f32_16x16x32_f16 v[178:181], v[30:33], v[114:117], v[6:9]
	v_mfma_f32_16x16x32_f16 v[6:9], v[18:21], v[118:121], 0
	v_mfma_f32_16x16x32_f16 v[22:25], v[22:25], v[122:125], v[6:9]
	v_mfma_f32_16x16x32_f16 v[6:9], v[26:29], v[118:121], 0
	v_mfma_f32_16x16x32_f16 v[182:185], v[30:33], v[122:125], v[6:9]
	s_barrier
; #define PG8_STAGE(bufoff, gbase, voff) do { if constexpr (ABL & 1) break; glds16s<(bufoff)>((voff)[0], (const void*)(gbase), ldsbw); glds16s<(bufoff) + 8192>((voff)[1], (const void*)(gbase), ldsbw); } while (0)
; #define PG8_LDA(dst, b, h) do { if constexpr (ABL & 4) break; _Pragma("unroll") for (int m = 0; m < 4; ++m) _Pragma("unroll") for (int k = 0; k < 2; ++k) dst[m][k] = *(const LAS f16x8*)(lds + PG8_SA(b, h) + aoff + m * 2048 + k * 1024); } while (0)
; #define PG8_LDB(dst, b, h) do { if constexpr (ABL & 4) break; _Pragma("unroll") for (int n = 0; n < 2; ++n) _Pragma("unroll") for (int k = 0; k < 2; ++k) dst[n][k] = *(const LAS f16x8*)(lds + PG8_SB(b, h) + boff + n * 2048 + k * 1024); } while (0)
; #define PG8_MMA(ai, bj, At, Bt) do { if constexpr (ABL & 2) break; __builtin_amdgcn_s_setprio(1); _Pragma("unroll") for (int m = 0; m < 4; ++m) _Pragma("unroll") for (int n = 0; n < 2; ++n) _Pragma("unroll") for (int k = 0; k < 2; ++k) \
;         acc[ai][bj][m][n] = __builtin_amdgcn_mfma_f32_16x16x32_f16(Bt[n][k], At[m][k], acc[ai][bj][m][n], 0, 0, 0); __builtin_amdgcn_s_setprio(0); } while (0)
; #define PG8_WAIT_V(n) asm volatile("s_waitcnt vmcnt(" #n ")" ::: "memory")
; #define PG8_WAIT_L(n) asm volatile("s_waitcnt lgkmcnt(" #n ")" ::: "memory")
; #define PG8_BAR __builtin_amdgcn_s_barrier()
; #define PG8_SCHED __builtin_amdgcn_sched_barrier(0)
;     ...
;             PG8_LDB(B0, 1, 0); PG8_LDB(B1, 1, 1); PG8_SCHED; PG8_LDA(At, 1, 0); if (!fin) PG8_STAGE(PG8_SA(0, 1), a2 + hstep, voffA);
;             if (!fin) PG8_WAIT_V(8); else PG8_WAIT_V(0); PG8_WAIT_L(0); PG8_BAR; PG8_MMA(0, 0, At, B0); PG8_MMA(0, 1, At, B1); PG8_BAR; PG8_SCHED;
;             PG8_LDA(At, 1, 1); if (!fin) { PG8_STAGE(PG8_SB(1, 0), b3, voffB); PG8_STAGE(PG8_SB(1, 1), b3 + hstep, voffB); PG8_STAGE(PG8_SA(1, 0), a3, voffA); }
;             if (!fin) PG8_WAIT_V(8); PG8_WAIT_L(0); PG8_BAR; PG8_MMA(1, 0, At, B0); PG8_MMA(1, 1, At, B1); PG8_BAR; PG8_SCHED;
	s_setprio 0
	s_nop 4
	ds_read_b128 v[6:9], v239
	ds_read_b128 v[26:29], v239 offset:1024
	ds_read_b128 v[186:189], v239 offset:2048
	ds_read_b128 v[190:193], v239 offset:3072
	ds_read_b128 v[206:209], v240
	ds_read_b128 v[210:213], v240 offset:1024
	ds_read_b128 v[214:217], v240 offset:2048
	ds_read_b128 v[218:221], v240 offset:3072
	ds_read_b128 v[14:17], v238 offset:32768
	ds_read_b128 v[18:21], v238 offset:33792
	ds_read_b128 v[30:33], v238 offset:34816
	ds_read_b128 v[222:225], v238 offset:35840
	ds_read_b128 v[226:229], v238 offset:36864
	ds_read_b128 v[242:245], v238 offset:37888
	ds_read_b128 v[246:249], v238 offset:38912
	ds_read_b128 v[250:253], v238 offset:39936
	s_add_u32 s62, s62, 0x40100
	s_addc_u32 s63, s63, 0
	s_add_u32 m0, s28, 0x4000
	s_nop 0
	global_load_lds_dwordx4 v232, s[62:63]
	s_nop 0
	s_add_u32 m0, s28, 0x6000
	s_nop 0
	global_load_lds_dwordx4 v234, s[62:63]
	s_waitcnt vmcnt(8)
	s_waitcnt lgkmcnt(0)
	s_barrier
	v_mfma_f32_16x16x32_f16 v[50:53], v[6:9], v[14:17], v[66:69]
	s_setprio 1
	v_mfma_f32_16x16x32_f16 v[118:121], v[26:29], v[18:21], v[50:53]
	v_mfma_f32_16x16x32_f16 v[50:53], v[186:189], v[14:17], v[70:73]
	v_mfma_f32_16x16x32_f16 v[114:117], v[190:193], v[18:21], v[50:53]
	v_mfma_f32_16x16x32_f16 v[50:53], v[6:9], v[30:33], v[74:77]
	v_mfma_f32_16x16x32_f16 v[102:105], v[26:29], v[222:225], v[50:53]
	v_mfma_f32_16x16x32_f16 v[50:53], v[186:189], v[30:33], v[78:81]
	v_mfma_f32_16x16x32_f16 v[98:101], v[190:193], v[222:225], v[50:53]
	v_mfma_f32_16x16x32_f16 v[50:53], v[6:9], v[226:229], v[82:85]
	v_mfma_f32_16x16x32_f16 v[86:89], v[26:29], v[242:245], v[50:53]
	v_mfma_f32_16x16x32_f16 v[50:53], v[186:189], v[226:229], v[90:93]
	v_mfma_f32_16x16x32_f16 v[78:81], v[190:193], v[242:245], v[50:53]
	v_mfma_f32_16x16x32_f16 v[50:53], v[6:9], v[246:249], v[94:97]
	v_mfma_f32_16x16x32_f16 v[58:61], v[26:29], v[250:253], v[50:53]
	v_mfma_f32_16x16x32_f16 v[50:53], v[186:189], v[246:249], v[106:109]
	v_mfma_f32_16x16x32_f16 v[50:53], v[190:193], v[250:253], v[50:53]
	v_mfma_f32_16x16x32_f16 v[66:69], v[206:209], v[14:17], v[110:113]
	v_mfma_f32_16x16x32_f16 v[126:129], v[210:213], v[18:21], v[66:69]
	v_mfma_f32_16x16x32_f16 v[14:17], v[214:217], v[14:17], v[34:37]
	v_mfma_f32_16x16x32_f16 v[122:125], v[218:221], v[18:21], v[14:17]
	v_mfma_f32_16x16x32_f16 v[14:17], v[206:209], v[30:33], v[38:41]
	v_mfma_f32_16x16x32_f16 v[110:113], v[210:213], v[222:225], v[14:17]
	v_mfma_f32_16x16x32_f16 v[14:17], v[214:217], v[30:33], v[42:45]
	v_mfma_f32_16x16x32_f16 v[106:109], v[218:221], v[222:225], v[14:17]
	v_mfma_f32_16x16x32_f16 v[14:17], v[206:209], v[226:229], v[46:49]
	v_mfma_f32_16x16x32_f16 v[94:97], v[210:213], v[242:245], v[14:17]
	v_mfma_f32_16x16x32_f16 v[14:17], v[214:217], v[226:229], v[54:57]
	v_mfma_f32_16x16x32_f16 v[90:93], v[218:221], v[242:245], v[14:17]
	v_mfma_f32_16x16x32_f16 v[14:17], v[206:209], v[246:249], v[130:133]
	v_mfma_f32_16x16x32_f16 v[74:77], v[210:213], v[250:253], v[14:17]
	v_mfma_f32_16x16x32_f16 v[14:17], v[214:217], v[246:249], v[62:65]
	v_mfma_f32_16x16x32_f16 v[66:69], v[218:221], v[250:253], v[14:17]
	s_barrier
	s_setprio 0
	ds_read_b128 v[38:41], v238 offset:49152
	ds_read_b128 v[42:45], v238 offset:50176
	ds_read_b128 v[130:133], v238 offset:51200
	ds_read_b128 v[222:225], v238 offset:52224
	ds_read_b128 v[226:229], v238 offset:53248
	ds_read_b128 v[242:245], v238 offset:54272
	ds_read_b128 v[246:249], v238 offset:55296
	ds_read_b128 v[250:253], v238 offset:56320
	s_add_u32 m0, s28, 0x18000
	s_nop 0
	global_load_lds_dwordx4 v233, s[26:27]
	s_nop 0
	s_add_u32 m0, s28, 0x1a000
	s_nop 0
	global_load_lds_dwordx4 v235, s[26:27]
	s_add_u32 s26, s6, 0x40180
	s_addc_u32 s27, s7, 0
	s_add_u32 m0, s28, 0x1c000
	s_nop 0
	global_load_lds_dwordx4 v233, s[26:27]
	s_nop 0
	s_add_u32 m0, s28, 0x1e000
	s_nop 0
	global_load_lds_dwordx4 v235, s[26:27]
	s_nop 0
	s_add_u32 m0, s28, 0x8000
	s_nop 0
	global_load_lds_dwordx4 v232, s[24:25]
	s_nop 0
	s_add_u32 m0, s28, 0xa000
	s_nop 0
	global_load_lds_dwordx4 v234, s[24:25]
	s_waitcnt vmcnt(8)
	s_waitcnt lgkmcnt(0)
	s_barrier
	v_mfma_f32_16x16x32_f16 v[14:17], v[6:9], v[38:41], v[134:137]
	s_setprio 1
	v_mfma_f32_16x16x32_f16 v[54:57], v[26:29], v[42:45], v[14:17]
	v_mfma_f32_16x16x32_f16 v[14:17], v[186:189], v[38:41], v[138:141]
	v_mfma_f32_16x16x32_f16 v[46:49], v[190:193], v[42:45], v[14:17]
	v_mfma_f32_16x16x32_f16 v[14:17], v[6:9], v[130:133], v[142:145]
	v_mfma_f32_16x16x32_f16 v[34:37], v[26:29], v[222:225], v[14:17]
	v_mfma_f32_16x16x32_f16 v[14:17], v[186:189], v[130:133], v[146:149]
	v_mfma_f32_16x16x32_f16 v[30:33], v[190:193], v[222:225], v[14:17]
	v_mfma_f32_16x16x32_f16 v[14:17], v[6:9], v[226:229], v[150:153]
	v_mfma_f32_16x16x32_f16 v[18:21], v[26:29], v[242:245], v[14:17]
	v_mfma_f32_16x16x32_f16 v[2:5], v[6:9], v[246:249], v[2:5]
	v_mfma_f32_16x16x32_f16 v[6:9], v[26:29], v[250:253], v[2:5]
	v_mfma_f32_16x16x32_f16 v[14:17], v[186:189], v[226:229], v[154:157]
	v_mfma_f32_16x16x32_f16 v[14:17], v[190:193], v[242:245], v[14:17]
	v_mfma_f32_16x16x32_f16 v[2:5], v[186:189], v[246:249], v[10:13]
	v_mfma_f32_16x16x32_f16 v[2:5], v[190:193], v[250:253], v[2:5]
	v_mfma_f32_16x16x32_f16 v[10:13], v[206:209], v[38:41], v[158:161]
	v_mfma_f32_16x16x32_f16 v[82:85], v[210:213], v[42:45], v[10:13]
	v_mfma_f32_16x16x32_f16 v[10:13], v[214:217], v[38:41], v[162:165]
	v_mfma_f32_16x16x32_f16 v[70:73], v[218:221], v[42:45], v[10:13]
	v_mfma_f32_16x16x32_f16 v[10:13], v[206:209], v[130:133], v[166:169]
	v_mfma_f32_16x16x32_f16 v[62:65], v[210:213], v[222:225], v[10:13]
	v_mfma_f32_16x16x32_f16 v[10:13], v[214:217], v[130:133], v[170:173]
	v_mfma_f32_16x16x32_f16 v[42:45], v[218:221], v[222:225], v[10:13]
	v_mfma_f32_16x16x32_f16 v[10:13], v[206:209], v[226:229], v[174:177]
	v_mfma_f32_16x16x32_f16 v[38:41], v[210:213], v[242:245], v[10:13]
	v_mfma_f32_16x16x32_f16 v[10:13], v[214:217], v[226:229], v[178:181]
	v_mfma_f32_16x16x32_f16 v[26:29], v[218:221], v[242:245], v[10:13]
	v_mfma_f32_16x16x32_f16 v[10:13], v[206:209], v[246:249], v[22:25]
	v_mfma_f32_16x16x32_f16 v[22:25], v[210:213], v[250:253], v[10:13]
	v_mfma_f32_16x16x32_f16 v[10:13], v[214:217], v[246:249], v[182:185]
	v_mfma_f32_16x16x32_f16 v[10:13], v[218:221], v[250:253], v[10:13]
	s_barrier
	s_setprio 0
	s_add_u32 s53, s6, 0x200
	s_addc_u32 s61, s7, 0
	s_mov_b32 s64, 0
	s_branch .LBB0_231

; #define PG8_STAGE(bufoff, gbase, voff) do { if constexpr (ABL & 1) break; glds16s<(bufoff)>((voff)[0], (const void*)(gbase), ldsbw); glds16s<(bufoff) + 8192>((voff)[1], (const void*)(gbase), ldsbw); } while (0)
; #define PG8_LDA(dst, b, h) do { if constexpr (ABL & 4) break; _Pragma("unroll") for (int m = 0; m < 4; ++m) _Pragma("unroll") for (int k = 0; k < 2; ++k) dst[m][k] = *(const LAS f16x8*)(lds + PG8_SA(b, h) + aoff + m * 2048 + k * 1024); } while (0)
; #define PG8_LDB(dst, b, h) do { if constexpr (ABL & 4) break; _Pragma("unroll") for (int n = 0; n < 2; ++n) _Pragma("unroll") for (int k = 0; k < 2; ++k) dst[n][k] = *(const LAS f16x8*)(lds + PG8_SB(b, h) + boff + n * 2048 + k * 1024); } while (0)
; #define PG8_MMAF(ai, bj, At, Bt) do { if (t == 0) PG8_MMA0(ai, bj, At, Bt); else PG8_MMA(ai, bj, At, Bt); } while (0)
; #define PG8_WAIT_V(n) asm volatile("s_waitcnt vmcnt(" #n ")" ::: "memory")
; #define PG8_WAIT_L(n) asm volatile("s_waitcnt lgkmcnt(" #n ")" ::: "memory")
; #define PG8_BAR __builtin_amdgcn_s_barrier()
; #define PG8_SCHED __builtin_amdgcn_sched_barrier(0)
;     ...
;             PG8_LDB(B0, 0, 0); PG8_LDB(B1, 0, 1); PG8_SCHED; PG8_LDA(At, 0, 0); PG8_STAGE(PG8_SA(1, 1), a1 + hstep, voffA);
;             PG8_WAIT_V(8); PG8_WAIT_L(0); PG8_BAR; PG8_MMAF(0, 0, At, B0); PG8_MMAF(0, 1, At, B1); PG8_BAR; PG8_SCHED;
;             const bool fin = last && !has_next;
;             PG8_LDA(At, 0, 1); if (!fin) { PG8_STAGE(PG8_SB(0, 0), b2, voffB); PG8_STAGE(PG8_SB(0, 1), b2 + hstep, voffB); PG8_STAGE(PG8_SA(0, 0), a2, voffA); }
;             if (!fin) PG8_WAIT_V(8); else PG8_WAIT_V(2); PG8_WAIT_L(0); PG8_BAR; PG8_MMAF(1, 0, At, B0); PG8_MMAF(1, 1, At, B1); PG8_BAR; PG8_SCHED;
.LBB0_878:
	s_ashr_i32 s45, s44, 31
	s_lshl_b64 s[8:9], s[44:45], 17
	s_add_u32 s48, s86, s8
	ds_read_b128 v[2:5], v1
	ds_read_b128 v[6:9], v1 offset:1024
	ds_read_b128 v[10:13], v1 offset:2048
	ds_read_b128 v[14:17], v1 offset:3072
	ds_read_b128 v[18:21], v234
	ds_read_b128 v[22:25], v234 offset:1024
	ds_read_b128 v[26:29], v234 offset:2048
	ds_read_b128 v[30:33], v234 offset:3072
	s_addc_u32 s49, s87, s9
	s_ashr_i32 s43, s42, 31
	s_lshl_b64 s[8:9], s[42:43], 17
	s_add_u32 s50, s70, s8
	s_addc_u32 s51, s71, s9
	s_add_u32 s26, s52, 0x100
	s_addc_u32 s27, s53, 0
	s_add_u32 s60, s54, 0x100
	s_addc_u32 s61, s55, 0
	s_add_u32 s8, s52, 0x180
	s_addc_u32 s9, s53, 0
	ds_read_b128 v[34:37], v235
	ds_read_b128 v[38:41], v235 offset:1024
	ds_read_b128 v[42:45], v235 offset:2048
	ds_read_b128 v[46:49], v235 offset:3072
	ds_read_b128 v[50:53], v235 offset:4096
	ds_read_b128 v[54:57], v235 offset:5120
	ds_read_b128 v[58:61], v235 offset:6144
	ds_read_b128 v[62:65], v235 offset:7168
	s_add_u32 s24, s54, 0x180
	s_addc_u32 s25, s55, 0
	s_add_u32 s62, s52, 0x10080
	s_addc_u32 s63, s53, 0
	s_add_u32 m0, s14, 0xc000
	s_nop 0
	global_load_lds_dwordx4 v230, s[62:63]
	s_nop 0
	s_add_u32 m0, s14, 0xe000
	s_nop 0
	global_load_lds_dwordx4 v232, s[62:63]
	s_waitcnt vmcnt(8)
	s_waitcnt lgkmcnt(0)
	s_barrier
	v_mfma_f32_16x16x32_f16 v[66:69], v[2:5], v[34:37], 0
	s_setprio 1
	v_mfma_f32_16x16x32_f16 v[66:69], v[6:9], v[38:41], v[66:69]
	v_mfma_f32_16x16x32_f16 v[70:73], v[10:13], v[34:37], 0
	v_mfma_f32_16x16x32_f16 v[70:73], v[14:17], v[38:41], v[70:73]
	v_mfma_f32_16x16x32_f16 v[82:85], v[2:5], v[50:53], 0
	v_mfma_f32_16x16x32_f16 v[82:85], v[6:9], v[54:57], v[82:85]
	v_mfma_f32_16x16x32_f16 v[86:89], v[10:13], v[50:53], 0
	v_mfma_f32_16x16x32_f16 v[86:89], v[14:17], v[54:57], v[86:89]
	v_mfma_f32_16x16x32_f16 v[90:93], v[2:5], v[58:61], 0
	v_mfma_f32_16x16x32_f16 v[90:93], v[6:9], v[62:65], v[90:93]
	v_mfma_f32_16x16x32_f16 v[94:97], v[10:13], v[58:61], 0
	v_mfma_f32_16x16x32_f16 v[94:97], v[14:17], v[62:65], v[94:97]
	v_mfma_f32_16x16x32_f16 v[74:77], v[2:5], v[42:45], 0
	v_mfma_f32_16x16x32_f16 v[74:77], v[6:9], v[46:49], v[74:77]
	v_mfma_f32_16x16x32_f16 v[78:81], v[10:13], v[42:45], 0
	v_mfma_f32_16x16x32_f16 v[78:81], v[14:17], v[46:49], v[78:81]
	v_mfma_f32_16x16x32_f16 v[98:101], v[18:21], v[34:37], 0
	v_mfma_f32_16x16x32_f16 v[98:101], v[22:25], v[38:41], v[98:101]
	v_mfma_f32_16x16x32_f16 v[34:37], v[26:29], v[34:37], 0
	v_mfma_f32_16x16x32_f16 v[34:37], v[30:33], v[38:41], v[34:37]
	v_mfma_f32_16x16x32_f16 v[38:41], v[18:21], v[42:45], 0
	v_mfma_f32_16x16x32_f16 v[38:41], v[22:25], v[46:49], v[38:41]
	v_mfma_f32_16x16x32_f16 v[42:45], v[26:29], v[42:45], 0
	v_mfma_f32_16x16x32_f16 v[42:45], v[30:33], v[46:49], v[42:45]
	v_mfma_f32_16x16x32_f16 v[46:49], v[18:21], v[50:53], 0
	v_mfma_f32_16x16x32_f16 v[46:49], v[22:25], v[54:57], v[46:49]
	v_mfma_f32_16x16x32_f16 v[50:53], v[26:29], v[50:53], 0
	v_mfma_f32_16x16x32_f16 v[50:53], v[30:33], v[54:57], v[50:53]
	v_mfma_f32_16x16x32_f16 v[54:57], v[18:21], v[58:61], 0
	v_mfma_f32_16x16x32_f16 v[54:57], v[22:25], v[62:65], v[54:57]
	v_mfma_f32_16x16x32_f16 v[58:61], v[26:29], v[58:61], 0
	v_mfma_f32_16x16x32_f16 v[58:61], v[30:33], v[62:65], v[58:61]
	s_barrier
	s_setprio 0
	ds_read_b128 v[62:65], v235 offset:16384
	ds_read_b128 v[102:105], v235 offset:17408
	ds_read_b128 v[106:109], v235 offset:18432
	ds_read_b128 v[110:113], v235 offset:19456
	ds_read_b128 v[114:117], v235 offset:20480
	ds_read_b128 v[118:121], v235 offset:21504
	ds_read_b128 v[122:125], v235 offset:22528
	ds_read_b128 v[126:129], v235 offset:23552
	s_add_u32 m0, s14, 0x10000
	s_nop 0
	global_load_lds_dwordx4 v231, s[60:61]
	s_nop 0
	s_add_u32 m0, s14, 0x12000
	s_nop 0
	global_load_lds_dwordx4 v233, s[60:61]
	s_add_u32 s60, s54, 0x10100
	s_addc_u32 s61, s55, 0
	s_add_u32 m0, s14, 0x14000
	s_nop 0
	global_load_lds_dwordx4 v231, s[60:61]
	s_nop 0
	s_add_u32 m0, s14, 0x16000
	s_nop 0
	global_load_lds_dwordx4 v233, s[60:61]
	s_nop 0
	s_add_u32 m0, s14, 0
	s_nop 0
	global_load_lds_dwordx4 v230, s[26:27]
	s_nop 0
	s_add_u32 m0, s14, 0x2000
	s_nop 0
	global_load_lds_dwordx4 v232, s[26:27]
	s_waitcnt vmcnt(8)
	s_waitcnt lgkmcnt(0)
	s_barrier
	v_mfma_f32_16x16x32_f16 v[130:133], v[2:5], v[62:65], 0
	s_setprio 1
	v_mfma_f32_16x16x32_f16 v[130:133], v[6:9], v[102:105], v[130:133]
	v_mfma_f32_16x16x32_f16 v[138:141], v[2:5], v[106:109], 0
	v_mfma_f32_16x16x32_f16 v[138:141], v[6:9], v[110:113], v[138:141]
	v_mfma_f32_16x16x32_f16 v[146:149], v[2:5], v[114:117], 0
	v_mfma_f32_16x16x32_f16 v[146:149], v[6:9], v[118:121], v[146:149]
	v_mfma_f32_16x16x32_f16 v[2:5], v[2:5], v[122:125], 0
	v_mfma_f32_16x16x32_f16 v[2:5], v[6:9], v[126:129], v[2:5]
	v_mfma_f32_16x16x32_f16 v[134:137], v[10:13], v[62:65], 0
	v_mfma_f32_16x16x32_f16 v[134:137], v[14:17], v[102:105], v[134:137]
	v_mfma_f32_16x16x32_f16 v[142:145], v[10:13], v[106:109], 0
	v_mfma_f32_16x16x32_f16 v[142:145], v[14:17], v[110:113], v[142:145]
	v_mfma_f32_16x16x32_f16 v[150:153], v[10:13], v[114:117], 0
	v_mfma_f32_16x16x32_f16 v[150:153], v[14:17], v[118:121], v[150:153]
	v_mfma_f32_16x16x32_f16 v[6:9], v[10:13], v[122:125], 0
	v_mfma_f32_16x16x32_f16 v[6:9], v[14:17], v[126:129], v[6:9]
	v_mfma_f32_16x16x32_f16 v[10:13], v[18:21], v[62:65], 0
	v_mfma_f32_16x16x32_f16 v[14:17], v[26:29], v[62:65], 0
	v_mfma_f32_16x16x32_f16 v[10:13], v[22:25], v[102:105], v[10:13]
	v_mfma_f32_16x16x32_f16 v[14:17], v[30:33], v[102:105], v[14:17]
	v_mfma_f32_16x16x32_f16 v[102:105], v[26:29], v[106:109], 0
	v_mfma_f32_16x16x32_f16 v[62:65], v[18:21], v[106:109], 0
	v_mfma_f32_16x16x32_f16 v[154:157], v[30:33], v[110:113], v[102:105]
	v_mfma_f32_16x16x32_f16 v[102:105], v[18:21], v[114:117], 0
	v_mfma_f32_16x16x32_f16 v[18:21], v[18:21], v[122:125], 0
	v_mfma_f32_16x16x32_f16 v[62:65], v[22:25], v[110:113], v[62:65]
	v_mfma_f32_16x16x32_f16 v[158:161], v[22:25], v[118:121], v[102:105]
	v_mfma_f32_16x16x32_f16 v[102:105], v[26:29], v[114:117], 0
	v_mfma_f32_16x16x32_f16 v[18:21], v[22:25], v[126:129], v[18:21]
	v_mfma_f32_16x16x32_f16 v[22:25], v[26:29], v[122:125], 0
	v_mfma_f32_16x16x32_f16 v[162:165], v[30:33], v[118:121], v[102:105]
	v_mfma_f32_16x16x32_f16 v[22:25], v[30:33], v[126:129], v[22:25]
	s_barrier
; #define PG8_STAGE(bufoff, gbase, voff) do { if constexpr (ABL & 1) break; glds16s<(bufoff)>((voff)[0], (const void*)(gbase), ldsbw); glds16s<(bufoff) + 8192>((voff)[1], (const void*)(gbase), ldsbw); } while (0)
; #define PG8_LDA(dst, b, h) do { if constexpr (ABL & 4) break; _Pragma("unroll") for (int m = 0; m < 4; ++m) _Pragma("unroll") for (int k = 0; k < 2; ++k) dst[m][k] = *(const LAS f16x8*)(lds + PG8_SA(b, h) + aoff + m * 2048 + k * 1024); } while (0)
; #define PG8_LDB(dst, b, h) do { if constexpr (ABL & 4) break; _Pragma("unroll") for (int n = 0; n < 2; ++n) _Pragma("unroll") for (int k = 0; k < 2; ++k) dst[n][k] = *(const LAS f16x8*)(lds + PG8_SB(b, h) + boff + n * 2048 + k * 1024); } while (0)
; #define PG8_MMA(ai, bj, At, Bt) do { if constexpr (ABL & 2) break; __builtin_amdgcn_s_setprio(1); _Pragma("unroll") for (int m = 0; m < 4; ++m) _Pragma("unroll") for (int n = 0; n < 2; ++n) _Pragma("unroll") for (int k = 0; k < 2; ++k) \
;         acc[ai][bj][m][n] = __builtin_amdgcn_mfma_f32_16x16x32_f16(Bt[n][k], At[m][k], acc[ai][bj][m][n], 0, 0, 0); __builtin_amdgcn_s_setprio(0); } while (0)
; #define PG8_WAIT_V(n) asm volatile("s_waitcnt vmcnt(" #n ")" ::: "memory")
; #define PG8_WAIT_L(n) asm volatile("s_waitcnt lgkmcnt(" #n ")" ::: "memory")
; #define PG8_BAR __builtin_amdgcn_s_barrier()
; #define PG8_SCHED __builtin_amdgcn_sched_barrier(0)
;     ...
;             PG8_LDB(B0, 1, 0); PG8_LDB(B1, 1, 1); PG8_SCHED; PG8_LDA(At, 1, 0); if (!fin) PG8_STAGE(PG8_SA(0, 1), a2 + hstep, voffA);
;             if (!fin) PG8_WAIT_V(8); else PG8_WAIT_V(0); PG8_WAIT_L(0); PG8_BAR; PG8_MMA(0, 0, At, B0); PG8_MMA(0, 1, At, B1); PG8_BAR; PG8_SCHED;
;             PG8_LDA(At, 1, 1); if (!fin) { PG8_STAGE(PG8_SB(1, 0), b3, voffB); PG8_STAGE(PG8_SB(1, 1), b3 + hstep, voffB); PG8_STAGE(PG8_SA(1, 0), a3, voffA); }
	s_setprio 0
	ds_read_b128 v[26:29], v236
	ds_read_b128 v[30:33], v236 offset:1024
	ds_read_b128 v[102:105], v236 offset:2048
	ds_read_b128 v[106:109], v236 offset:3072
	ds_read_b128 v[166:169], v237
	ds_read_b128 v[170:173], v237 offset:1024
	ds_read_b128 v[174:177], v237 offset:2048
	ds_read_b128 v[178:181], v237 offset:3072
	ds_read_b128 v[110:113], v235 offset:32768
	ds_read_b128 v[114:117], v235 offset:33792
	ds_read_b128 v[118:121], v235 offset:34816
	ds_read_b128 v[122:125], v235 offset:35840
	ds_read_b128 v[126:129], v235 offset:36864
	ds_read_b128 v[182:185], v235 offset:37888
	ds_read_b128 v[186:189], v235 offset:38912
	ds_read_b128 v[190:193], v235 offset:39936
	s_add_u32 s26, s52, 0x10100
	s_addc_u32 s27, s53, 0
	s_add_u32 m0, s14, 0x4000
	s_nop 0
	global_load_lds_dwordx4 v230, s[26:27]
	s_nop 0
	s_add_u32 m0, s14, 0x6000
	s_nop 0
	global_load_lds_dwordx4 v232, s[26:27]
	s_waitcnt vmcnt(8)
	s_waitcnt lgkmcnt(0)
	s_barrier
	v_mfma_f32_16x16x32_f16 v[82:85], v[26:29], v[126:129], v[82:85]
	s_setprio 1
	v_mfma_f32_16x16x32_f16 v[194:197], v[30:33], v[182:185], v[82:85]
	v_mfma_f32_16x16x32_f16 v[82:85], v[102:105], v[126:129], v[86:89]
	v_mfma_f32_16x16x32_f16 v[198:201], v[106:109], v[182:185], v[82:85]
	v_mfma_f32_16x16x32_f16 v[66:69], v[26:29], v[110:113], v[66:69]
	v_mfma_f32_16x16x32_f16 v[66:69], v[30:33], v[114:117], v[66:69]
	v_mfma_f32_16x16x32_f16 v[70:73], v[102:105], v[110:113], v[70:73]
	v_mfma_f32_16x16x32_f16 v[70:73], v[106:109], v[114:117], v[70:73]
	v_mfma_f32_16x16x32_f16 v[82:85], v[26:29], v[186:189], v[90:93]
	v_mfma_f32_16x16x32_f16 v[202:205], v[30:33], v[190:193], v[82:85]
	v_mfma_f32_16x16x32_f16 v[74:77], v[26:29], v[118:121], v[74:77]
	v_mfma_f32_16x16x32_f16 v[74:77], v[30:33], v[122:125], v[74:77]
	v_mfma_f32_16x16x32_f16 v[78:81], v[102:105], v[118:121], v[78:81]
	v_mfma_f32_16x16x32_f16 v[78:81], v[106:109], v[122:125], v[78:81]
	v_mfma_f32_16x16x32_f16 v[82:85], v[102:105], v[186:189], v[94:97]
	v_mfma_f32_16x16x32_f16 v[206:209], v[106:109], v[190:193], v[82:85]
	v_mfma_f32_16x16x32_f16 v[34:37], v[174:177], v[110:113], v[34:37]
	v_mfma_f32_16x16x32_f16 v[214:217], v[178:181], v[114:117], v[34:37]
	v_mfma_f32_16x16x32_f16 v[34:37], v[166:169], v[118:121], v[38:41]
	v_mfma_f32_16x16x32_f16 v[218:221], v[170:173], v[122:125], v[34:37]
	v_mfma_f32_16x16x32_f16 v[34:37], v[174:177], v[118:121], v[42:45]
	v_mfma_f32_16x16x32_f16 v[222:225], v[178:181], v[122:125], v[34:37]
	v_mfma_f32_16x16x32_f16 v[34:37], v[166:169], v[126:129], v[46:49]
	v_mfma_f32_16x16x32_f16 v[238:241], v[170:173], v[182:185], v[34:37]
	v_mfma_f32_16x16x32_f16 v[34:37], v[174:177], v[126:129], v[50:53]
	v_mfma_f32_16x16x32_f16 v[182:185], v[178:181], v[182:185], v[34:37]
	v_mfma_f32_16x16x32_f16 v[34:37], v[166:169], v[186:189], v[54:57]
	v_mfma_f32_16x16x32_f16 v[242:245], v[170:173], v[190:193], v[34:37]
	v_mfma_f32_16x16x32_f16 v[34:37], v[174:177], v[186:189], v[58:61]
	v_mfma_f32_16x16x32_f16 v[186:189], v[178:181], v[190:193], v[34:37]
	v_mfma_f32_16x16x32_f16 v[82:85], v[166:169], v[110:113], v[98:101]
	v_mfma_f32_16x16x32_f16 v[210:213], v[170:173], v[114:117], v[82:85]
	s_barrier
	s_setprio 0
	ds_read_b128 v[42:45], v235 offset:49152
	ds_read_b128 v[46:49], v235 offset:50176
	ds_read_b128 v[50:53], v235 offset:51200
	ds_read_b128 v[54:57], v235 offset:52224
	ds_read_b128 v[58:61], v235 offset:53248
	ds_read_b128 v[126:129], v235 offset:54272
	ds_read_b128 v[190:193], v235 offset:55296
	ds_read_b128 v[246:249], v235 offset:56320
	s_add_u32 m0, s14, 0x18000
	s_nop 0
	global_load_lds_dwordx4 v231, s[24:25]
	s_nop 0
	s_add_u32 m0, s14, 0x1a000
	s_nop 0
	global_load_lds_dwordx4 v233, s[24:25]
	s_add_u32 s24, s54, 0x10180
	s_addc_u32 s25, s55, 0
	s_add_u32 m0, s14, 0x1c000
	s_nop 0
	global_load_lds_dwordx4 v231, s[24:25]
	s_nop 0
	s_add_u32 m0, s14, 0x1e000
	s_nop 0
	global_load_lds_dwordx4 v233, s[24:25]
	s_nop 0
	s_add_u32 m0, s14, 0x8000
	s_nop 0
	global_load_lds_dwordx4 v230, s[8:9]
	s_nop 0
	s_add_u32 m0, s14, 0xa000
	s_nop 0
	global_load_lds_dwordx4 v232, s[8:9]
	s_waitcnt vmcnt(8)
	s_waitcnt lgkmcnt(0)
	s_barrier
; #define PG8_STAGE(bufoff, gbase, voff) do { if constexpr (ABL & 1) break; glds16s<(bufoff)>((voff)[0], (const void*)(gbase), ldsbw); glds16s<(bufoff) + 8192>((voff)[1], (const void*)(gbase), ldsbw); } while (0)
; #define PG8_LDA(dst, b, h) do { if constexpr (ABL & 4) break; _Pragma("unroll") for (int m = 0; m < 4; ++m) _Pragma("unroll") for (int k = 0; k < 2; ++k) dst[m][k] = *(const LAS f16x8*)(lds + PG8_SA(b, h) + aoff + m * 2048 + k * 1024); } while (0)
; #define PG8_LDB(dst, b, h) do { if constexpr (ABL & 4) break; _Pragma("unroll") for (int n = 0; n < 2; ++n) _Pragma("unroll") for (int k = 0; k < 2; ++k) dst[n][k] = *(const LAS f16x8*)(lds + PG8_SB(b, h) + boff + n * 2048 + k * 1024); } while (0)
; #define PG8_MMA(ai, bj, At, Bt) do { if constexpr (ABL & 2) break; __builtin_amdgcn_s_setprio(1); _Pragma("unroll") for (int m = 0; m < 4; ++m) _Pragma("unroll") for (int n = 0; n < 2; ++n) _Pragma("unroll") for (int k = 0; k < 2; ++k) \
;         acc[ai][bj][m][n] = __builtin_amdgcn_mfma_f32_16x16x32_f16(Bt[n][k], At[m][k], acc[ai][bj][m][n], 0, 0, 0); __builtin_amdgcn_s_setprio(0); } while (0)
; #define PG8_WAIT_V(n) asm volatile("s_waitcnt vmcnt(" #n ")" ::: "memory")
;     ...
;             PG8_LDB(B0, 0, 0); PG8_LDB(B1, 0, 1); PG8_SCHED; PG8_LDA(At, 0, 0); PG8_STAGE(PG8_SA(1, 1), a1 + hstep, voffA);
;             PG8_WAIT_V(8); PG8_WAIT_L(0); PG8_BAR; PG8_MMAF(0, 0, At, B0); PG8_MMAF(0, 1, At, B1); PG8_BAR; PG8_SCHED;
;             const bool fin = last && !has_next;
;             PG8_LDA(At, 0, 1); if (!fin) { PG8_STAGE(PG8_SB(0, 0), b2, voffB); PG8_STAGE(PG8_SB(0, 1), b2 + hstep, voffB); PG8_STAGE(PG8_SA(0, 0), a2, voffA); }
;             if (!fin) PG8_WAIT_V(8); else PG8_WAIT_V(2); PG8_WAIT_L(0); PG8_BAR; PG8_MMAF(1, 0, At, B0); PG8_MMAF(1, 1, At, B1); PG8_BAR; PG8_SCHED;
;             PG8_LDB(B0, 1, 0); PG8_LDB(B1, 1, 1); PG8_SCHED; PG8_LDA(At, 1, 0); if (!fin) PG8_STAGE(PG8_SA(0, 1), a2 + hstep, voffA);
;             if (!fin) PG8_WAIT_V(8); else PG8_WAIT_V(0); PG8_WAIT_L(0); PG8_BAR; PG8_MMA(0, 0, At, B0); PG8_MMA(0, 1, At, B1); PG8_BAR; PG8_SCHED;
;             PG8_LDA(At, 1, 1); if (!fin) { PG8_STAGE(PG8_SB(1, 0), b3, voffB); PG8_STAGE(PG8_SB(1, 1), b3 + hstep, voffB); PG8_STAGE(PG8_SA(1, 0), a3, voffA); }
;             if (!fin) PG8_WAIT_V(8); PG8_WAIT_L(0); PG8_BAR; PG8_MMA(1, 0, At, B0); PG8_MMA(1, 1, At, B1); PG8_BAR; PG8_SCHED;
	v_mfma_f32_16x16x32_f16 v[2:5], v[26:29], v[190:193], v[2:5]
	s_setprio 1
	v_mfma_f32_16x16x32_f16 v[98:101], v[30:33], v[246:249], v[2:5]
	v_mfma_f32_16x16x32_f16 v[34:37], v[26:29], v[42:45], v[130:133]
	v_mfma_f32_16x16x32_f16 v[34:37], v[30:33], v[46:49], v[34:37]
	v_mfma_f32_16x16x32_f16 v[38:41], v[102:105], v[42:45], v[134:137]
	v_mfma_f32_16x16x32_f16 v[38:41], v[106:109], v[46:49], v[38:41]
	v_mfma_f32_16x16x32_f16 v[82:85], v[26:29], v[50:53], v[138:141]
	v_mfma_f32_16x16x32_f16 v[82:85], v[30:33], v[54:57], v[82:85]
	v_mfma_f32_16x16x32_f16 v[86:89], v[102:105], v[50:53], v[142:145]
	v_mfma_f32_16x16x32_f16 v[86:89], v[106:109], v[54:57], v[86:89]
	v_mfma_f32_16x16x32_f16 v[90:93], v[26:29], v[58:61], v[146:149]
	v_mfma_f32_16x16x32_f16 v[90:93], v[30:33], v[126:129], v[90:93]
	v_mfma_f32_16x16x32_f16 v[94:97], v[102:105], v[58:61], v[150:153]
	v_mfma_f32_16x16x32_f16 v[94:97], v[106:109], v[126:129], v[94:97]
	v_mfma_f32_16x16x32_f16 v[2:5], v[102:105], v[190:193], v[6:9]
	v_mfma_f32_16x16x32_f16 v[102:105], v[106:109], v[246:249], v[2:5]
	v_mfma_f32_16x16x32_f16 v[2:5], v[166:169], v[42:45], v[10:13]
	v_mfma_f32_16x16x32_f16 v[106:109], v[170:173], v[46:49], v[2:5]
	v_mfma_f32_16x16x32_f16 v[2:5], v[174:177], v[42:45], v[14:17]
	v_mfma_f32_16x16x32_f16 v[110:113], v[178:181], v[46:49], v[2:5]
	v_mfma_f32_16x16x32_f16 v[2:5], v[166:169], v[50:53], v[62:65]
	v_mfma_f32_16x16x32_f16 v[114:117], v[170:173], v[54:57], v[2:5]
	v_mfma_f32_16x16x32_f16 v[2:5], v[174:177], v[50:53], v[154:157]
	v_mfma_f32_16x16x32_f16 v[118:121], v[178:181], v[54:57], v[2:5]
	v_mfma_f32_16x16x32_f16 v[2:5], v[166:169], v[58:61], v[158:161]
	v_mfma_f32_16x16x32_f16 v[122:125], v[170:173], v[126:129], v[2:5]
	v_mfma_f32_16x16x32_f16 v[2:5], v[174:177], v[58:61], v[162:165]
	v_mfma_f32_16x16x32_f16 v[126:129], v[178:181], v[126:129], v[2:5]
	v_mfma_f32_16x16x32_f16 v[2:5], v[166:169], v[190:193], v[18:21]
	v_mfma_f32_16x16x32_f16 v[130:133], v[170:173], v[246:249], v[2:5]
	v_mfma_f32_16x16x32_f16 v[2:5], v[174:177], v[190:193], v[22:25]
	v_mfma_f32_16x16x32_f16 v[134:137], v[178:181], v[246:249], v[2:5]
	s_barrier
	s_setprio 0
	ds_read_b128 v[154:157], v1
	ds_read_b128 v[158:161], v1 offset:1024
	ds_read_b128 v[162:165], v1 offset:2048
	ds_read_b128 v[166:169], v1 offset:3072
	ds_read_b128 v[138:141], v234
	ds_read_b128 v[142:145], v234 offset:1024
	ds_read_b128 v[146:149], v234 offset:2048
	ds_read_b128 v[150:153], v234 offset:3072
	ds_read_b128 v[46:49], v235
	ds_read_b128 v[50:53], v235 offset:1024
	ds_read_b128 v[54:57], v235 offset:2048
	ds_read_b128 v[58:61], v235 offset:3072
	ds_read_b128 v[62:65], v235 offset:4096
	ds_read_b128 v[170:173], v235 offset:5120
	ds_read_b128 v[174:177], v235 offset:6144
	ds_read_b128 v[178:181], v235 offset:7168
	s_add_u32 s8, s52, 0x10180
	s_addc_u32 s9, s53, 0
	s_add_u32 m0, s14, 0xc000
	s_nop 0
	global_load_lds_dwordx4 v230, s[8:9]
	s_nop 0
	s_add_u32 m0, s14, 0xe000
	s_nop 0
	global_load_lds_dwordx4 v232, s[8:9]
	s_waitcnt vmcnt(8)
	s_waitcnt lgkmcnt(0)
	s_barrier
	v_mfma_f32_16x16x32_f16 v[2:5], v[154:157], v[46:49], v[66:69]
	s_setprio 1
	v_mfma_f32_16x16x32_f16 v[2:5], v[158:161], v[50:53], v[2:5]
	v_mfma_f32_16x16x32_f16 v[6:9], v[162:165], v[46:49], v[70:73]
	v_mfma_f32_16x16x32_f16 v[6:9], v[166:169], v[50:53], v[6:9]
	v_mfma_f32_16x16x32_f16 v[10:13], v[154:157], v[54:57], v[74:77]
	v_mfma_f32_16x16x32_f16 v[10:13], v[158:161], v[58:61], v[10:13]
	v_mfma_f32_16x16x32_f16 v[14:17], v[162:165], v[54:57], v[78:81]
	v_mfma_f32_16x16x32_f16 v[14:17], v[166:169], v[58:61], v[14:17]
	v_mfma_f32_16x16x32_f16 v[18:21], v[154:157], v[62:65], v[194:197]
	v_mfma_f32_16x16x32_f16 v[18:21], v[158:161], v[170:173], v[18:21]
	v_mfma_f32_16x16x32_f16 v[22:25], v[162:165], v[62:65], v[198:201]
	v_mfma_f32_16x16x32_f16 v[22:25], v[166:169], v[170:173], v[22:25]
	v_mfma_f32_16x16x32_f16 v[26:29], v[154:157], v[174:177], v[202:205]
	v_mfma_f32_16x16x32_f16 v[26:29], v[158:161], v[178:181], v[26:29]
	v_mfma_f32_16x16x32_f16 v[30:33], v[162:165], v[174:177], v[206:209]
	v_mfma_f32_16x16x32_f16 v[30:33], v[166:169], v[178:181], v[30:33]
	v_mfma_f32_16x16x32_f16 v[42:45], v[138:141], v[46:49], v[210:213]
	v_mfma_f32_16x16x32_f16 v[42:45], v[142:145], v[50:53], v[42:45]
	v_mfma_f32_16x16x32_f16 v[46:49], v[146:149], v[46:49], v[214:217]
	v_mfma_f32_16x16x32_f16 v[46:49], v[150:153], v[50:53], v[46:49]
	v_mfma_f32_16x16x32_f16 v[50:53], v[138:141], v[54:57], v[218:221]
	v_mfma_f32_16x16x32_f16 v[50:53], v[142:145], v[58:61], v[50:53]
	v_mfma_f32_16x16x32_f16 v[54:57], v[146:149], v[54:57], v[222:225]
	v_mfma_f32_16x16x32_f16 v[54:57], v[150:153], v[58:61], v[54:57]
	v_mfma_f32_16x16x32_f16 v[58:61], v[138:141], v[62:65], v[238:241]
	v_mfma_f32_16x16x32_f16 v[58:61], v[142:145], v[170:173], v[58:61]
	v_mfma_f32_16x16x32_f16 v[62:65], v[146:149], v[62:65], v[182:185]
	v_mfma_f32_16x16x32_f16 v[62:65], v[150:153], v[170:173], v[62:65]
	v_mfma_f32_16x16x32_f16 v[66:69], v[138:141], v[174:177], v[242:245]
	v_mfma_f32_16x16x32_f16 v[66:69], v[142:145], v[178:181], v[66:69]
	v_mfma_f32_16x16x32_f16 v[70:73], v[146:149], v[174:177], v[186:189]
	v_mfma_f32_16x16x32_f16 v[70:73], v[150:153], v[178:181], v[70:73]
	s_barrier
	s_setprio 0
	ds_read_b128 v[194:197], v235 offset:16384
	ds_read_b128 v[198:201], v235 offset:17408
	ds_read_b128 v[186:189], v235 offset:18432
	ds_read_b128 v[190:193], v235 offset:19456
	ds_read_b128 v[178:181], v235 offset:20480
	ds_read_b128 v[182:185], v235 offset:21504
	ds_read_b128 v[170:173], v235 offset:22528
	ds_read_b128 v[174:177], v235 offset:23552
	s_mov_b64 s[8:9], -1
	s_and_b64 vcc, exec, s[4:5]
	s_cbranch_vccz .LBB0_880
	s_waitcnt vmcnt(2)
	s_mov_b64 s[8:9], 0
